# MoBA item prologue: first K/V^T tile global loads issued right after the gating scores (before top-3 selection and step scan)
# speedup vs baseline: 1.0095x; 1.0028x over previous
.LBB0_94:
	s_waitcnt lgkmcnt(8)
	v_lshlrev_b32_e32 v64, 16, v4
	v_and_b32_e32 v65, 0xffff0000, v4
	v_lshlrev_b32_e32 v66, 16, v5
	v_and_b32_e32 v67, 0xffff0000, v5
	v_lshlrev_b32_e32 v68, 16, v6
	v_and_b32_e32 v69, 0xffff0000, v6
	v_lshlrev_b32_e32 v70, 16, v7
	v_and_b32_e32 v71, 0xffff0000, v7
	v_pk_mul_f32 v[46:47], v[10:11], v[64:65] op_sel:[0,1] op_sel_hi:[1,1]
	v_pk_mul_f32 v[48:49], v[14:15], v[66:67] op_sel:[0,1] op_sel_hi:[1,1]
	v_pk_mul_f32 v[50:51], v[18:19], v[68:69] op_sel:[0,1] op_sel_hi:[1,1]
	v_pk_mul_f32 v[52:53], v[22:23], v[70:71] op_sel:[0,1] op_sel_hi:[1,1]
	v_pk_mul_f32 v[54:55], v[26:27], v[64:65] op_sel:[0,1] op_sel_hi:[1,1]
	v_pk_mul_f32 v[56:57], v[30:31], v[66:67] op_sel:[0,1] op_sel_hi:[1,1]
	v_pk_mul_f32 v[58:59], v[34:35], v[68:69] op_sel:[0,1] op_sel_hi:[1,1]
	v_pk_mul_f32 v[60:61], v[90:91], v[70:71] op_sel:[0,1] op_sel_hi:[1,1]
	v_pk_fma_f32 v[46:47], v[8:9], v[64:65], v[46:47] op_sel_hi:[1,0,1]
	v_pk_fma_f32 v[48:49], v[12:13], v[66:67], v[48:49] op_sel_hi:[1,0,1]
	v_pk_fma_f32 v[50:51], v[16:17], v[68:69], v[50:51] op_sel_hi:[1,0,1]
	v_pk_fma_f32 v[52:53], v[20:21], v[70:71], v[52:53] op_sel_hi:[1,0,1]
	v_pk_fma_f32 v[54:55], v[24:25], v[64:65], v[54:55] op_sel_hi:[1,0,1]
	v_pk_fma_f32 v[56:57], v[28:29], v[66:67], v[56:57] op_sel_hi:[1,0,1]
	v_pk_fma_f32 v[58:59], v[32:33], v[68:69], v[58:59] op_sel_hi:[1,0,1]
	v_pk_fma_f32 v[60:61], v[88:89], v[70:71], v[60:61] op_sel_hi:[1,0,1]
	v_pk_add_f32 v[46:47], v[46:47], v[48:49]
	v_pk_add_f32 v[54:55], v[54:55], v[56:57]
	v_pk_add_f32 v[46:47], v[46:47], v[50:51]
	v_pk_add_f32 v[54:55], v[54:55], v[58:59]
	v_pk_add_f32 v[46:47], v[46:47], v[52:53]
	v_pk_add_f32 v[54:55], v[54:55], v[60:61]
	v_pk_add_f32 v[40:41], v[40:41], v[46:47]
	v_pk_add_f32 v[42:43], v[42:43], v[54:55]
	v_add_u32_e32 v202, 16, v202
	v_add_u32_e32 v203, 64, v203
	s_waitcnt lgkmcnt(0)
	ds_read_b128 v[4:7], v202
	ds_read_b128 v[8:11], v203
	ds_read_b128 v[12:15], v203 offset:16
	ds_read_b128 v[16:19], v203 offset:32
	ds_read_b128 v[20:23], v203 offset:48
	ds_read_b128 v[24:27], v203 offset:1024
	ds_read_b128 v[28:31], v203 offset:1040
	ds_read_b128 v[32:35], v203 offset:1056
	ds_read_b128 v[88:91], v203 offset:1072
	v_pk_mul_f32 v[46:47], v[94:95], v[64:65] op_sel:[0,1] op_sel_hi:[1,1]
	v_pk_mul_f32 v[48:49], v[98:99], v[66:67] op_sel:[0,1] op_sel_hi:[1,1]
	v_pk_mul_f32 v[50:51], v[102:103], v[68:69] op_sel:[0,1] op_sel_hi:[1,1]
	v_pk_mul_f32 v[52:53], v[106:107], v[70:71] op_sel:[0,1] op_sel_hi:[1,1]
	v_pk_mul_f32 v[54:55], v[110:111], v[64:65] op_sel:[0,1] op_sel_hi:[1,1]
	v_pk_mul_f32 v[56:57], v[114:115], v[66:67] op_sel:[0,1] op_sel_hi:[1,1]
	v_pk_mul_f32 v[58:59], v[196:197], v[68:69] op_sel:[0,1] op_sel_hi:[1,1]
	v_pk_mul_f32 v[60:61], v[200:201], v[70:71] op_sel:[0,1] op_sel_hi:[1,1]
	v_pk_fma_f32 v[46:47], v[92:93], v[64:65], v[46:47] op_sel_hi:[1,0,1]
	v_pk_fma_f32 v[48:49], v[96:97], v[66:67], v[48:49] op_sel_hi:[1,0,1]
	v_pk_fma_f32 v[50:51], v[100:101], v[68:69], v[50:51] op_sel_hi:[1,0,1]
	v_pk_fma_f32 v[52:53], v[104:105], v[70:71], v[52:53] op_sel_hi:[1,0,1]
	v_pk_fma_f32 v[54:55], v[108:109], v[64:65], v[54:55] op_sel_hi:[1,0,1]
	v_pk_fma_f32 v[56:57], v[112:113], v[66:67], v[56:57] op_sel_hi:[1,0,1]
	v_pk_fma_f32 v[58:59], v[194:195], v[68:69], v[58:59] op_sel_hi:[1,0,1]
	v_pk_fma_f32 v[60:61], v[198:199], v[70:71], v[60:61] op_sel_hi:[1,0,1]
	v_pk_add_f32 v[46:47], v[46:47], v[48:49]
	v_pk_add_f32 v[54:55], v[54:55], v[56:57]
	v_pk_add_f32 v[46:47], v[46:47], v[50:51]
	v_pk_add_f32 v[54:55], v[54:55], v[58:59]
	v_pk_add_f32 v[46:47], v[46:47], v[52:53]
	v_pk_add_f32 v[54:55], v[54:55], v[60:61]
	v_pk_add_f32 v[38:39], v[38:39], v[46:47]
	v_pk_add_f32 v[36:37], v[36:37], v[54:55]
	s_waitcnt lgkmcnt(7)
	ds_read_b128 v[92:95], v203 offset:2048
	ds_read_b128 v[96:99], v203 offset:2064
	ds_read_b128 v[100:103], v203 offset:2080
	ds_read_b128 v[104:107], v203 offset:2096
	ds_read_b128 v[108:111], v203 offset:3072
	ds_read_b128 v[112:115], v203 offset:3088
	ds_read_b128 v[194:197], v203 offset:3104
	ds_read_b128 v[198:201], v203 offset:3120
	s_add_i32 s0, s0, -1
	s_cmp_lg_u32 s0, 0
	s_cbranch_scc1 .LBB0_94
	v_swap_b32 v40, v41
	s_ashr_i32 s47, s8, 1
	v_cmp_gt_i32_e32 vcc, s47, v128
	s_nop 1
	v_cndmask_b32_e32 v40, v215, v40, vcc
	v_cmp_gt_i32_e32 vcc, s47, v1
	s_nop 1
	v_cndmask_b32_e32 v41, v215, v41, vcc
	v_cmp_gt_i32_e32 vcc, s47, v121
	ds_write2_b32 v184, v41, v40 offset1:1
	s_nop 0
	v_cndmask_b32_e32 v40, v215, v43, vcc
	v_cmp_gt_i32_e32 vcc, s47, v130
	s_nop 1
	v_cndmask_b32_e32 v41, v215, v42, vcc
	v_cmp_gt_i32_e32 vcc, s47, v129
	ds_write2_b32 v185, v41, v40 offset1:1
	s_nop 0
	v_cndmask_b32_e32 v39, v215, v39, vcc
	v_cmp_gt_i32_e32 vcc, s47, v132
	s_nop 1
	v_cndmask_b32_e32 v38, v215, v38, vcc
	v_cmp_gt_i32_e32 vcc, s47, v131
	ds_write2_b32 v186, v38, v39 offset1:1
	s_nop 0
	v_cndmask_b32_e32 v37, v215, v37, vcc
	v_cmp_gt_i32_e32 vcc, s47, v134
	s_nop 1
	v_cndmask_b32_e32 v36, v215, v36, vcc
	ds_write2_b32 v187, v36, v37 offset1:1
	s_waitcnt lgkmcnt(0)
	s_lshl_b32 s82, s47, 8
	s_ashr_i32 s83, s82, 31
	v_lshl_add_u64 v[4:5], v[140:141], 0, s[82:83]
	v_mov_b64_e32 v[6:7], s[88:89]
	v_lshl_add_u64 v[28:29], s[82:83], 1, v[118:119]
	v_mad_u64_u32 v[6:7], s[82:83], v4, s72, v[6:7]
	v_mad_i32_i24 v7, v5, s72, v7
	v_lshl_add_u64 v[4:5], v[6:7], 0, s[20:21]
	v_lshl_add_u64 v[30:31], v[4:5], 0, v[2:3]
	v_add_co_u32_e32 v4, vcc, s3, v30
	s_mov_b32 s87, 0x3d000
	s_nop 0
	v_addc_co_u32_e32 v5, vcc, 0, v31, vcc
	v_add_co_u32_e32 v12, vcc, s87, v30
	v_lshl_add_u64 v[8:9], v[28:29], 0, v[146:147]
	s_nop 0
	v_addc_co_u32_e32 v13, vcc, 0, v31, vcc
	v_add_co_u32_e32 v20, vcc, 0x79000, v30
	v_lshl_add_u64 v[16:17], v[28:29], 0, v[148:149]
	s_nop 0
	v_addc_co_u32_e32 v21, vcc, 0, v31, vcc
	v_add_co_u32_e32 v30, vcc, 0xb5000, v30
	v_lshl_add_u64 v[24:25], v[28:29], 0, v[150:151]
	s_nop 0
	v_addc_co_u32_e32 v31, vcc, 0, v31, vcc
	v_lshl_add_u64 v[32:33], v[28:29], 0, v[152:153]
	global_load_dwordx4 v[4:7], v[4:5], off offset:1024
	s_nop 0
	global_load_dwordx4 v[8:11], v[8:9], off
	s_nop 0
	global_load_dwordx4 v[12:15], v[12:13], off offset:1024
	s_nop 0
	global_load_dwordx4 v[16:19], v[16:17], off
	s_nop 0
	global_load_dwordx4 v[20:23], v[20:21], off offset:1024
	s_nop 0
	global_load_dwordx4 v[24:27], v[24:25], off
	s_nop 0
	global_load_dwordx4 v[28:31], v[30:31], off offset:1024
	s_nop 0
	global_load_dwordx4 v[32:35], v[32:33], off
	s_barrier
	s_and_saveexec_b64 s[0:1], s[4:5]
	s_cbranch_execz .LBB0_97
	ds_read2_b32 v[36:37], v191 offset1:1
	ds_read2_b32 v[38:39], v191 offset0:2 offset1:3
	ds_read2_b32 v[40:41], v191 offset0:4 offset1:5
	ds_read2_b32 v[42:43], v191 offset0:6 offset1:7
	ds_read2_b32 v[44:45], v191 offset0:8 offset1:9
	ds_read2_b32 v[46:47], v191 offset0:10 offset1:11
	ds_read2_b32 v[48:49], v191 offset0:12 offset1:13
	ds_read2_b32 v[50:51], v191 offset0:14 offset1:15
	ds_read2_b32 v[54:55], v191 offset0:16 offset1:17
	ds_read2_b32 v[56:57], v191 offset0:18 offset1:19
	ds_read2_b32 v[58:59], v191 offset0:20 offset1:21
	ds_read2_b32 v[60:61], v191 offset0:22 offset1:23
	ds_read2_b32 v[62:63], v191 offset0:24 offset1:25
	ds_read2_b32 v[64:65], v191 offset0:26 offset1:27
	ds_read2_b32 v[66:67], v191 offset0:28 offset1:29
	ds_read2_b32 v[68:69], v191 offset0:30 offset1:31
	s_waitcnt lgkmcnt(14)
	v_cmp_nlg_f32_e32 vcc, s73, v36
	s_nop 1
	v_cndmask_b32_e32 v70, v36, v215, vcc
	v_cndmask_b32_e64 v53, 0, -1, vcc
	v_cmp_gt_f32_e32 vcc, v37, v70
	s_nop 1
	v_cndmask_b32_e32 v70, v70, v37, vcc
	v_cndmask_b32_e64 v53, v53, 1, vcc
	v_cmp_gt_f32_e32 vcc, v38, v70
	s_nop 1
	v_cndmask_b32_e32 v70, v70, v38, vcc
	v_cndmask_b32_e64 v53, v53, 2, vcc
	v_cmp_gt_f32_e32 vcc, v39, v70
	s_nop 1
	v_cndmask_b32_e32 v70, v70, v39, vcc
	v_cndmask_b32_e64 v53, v53, 3, vcc
	s_waitcnt lgkmcnt(13)
	v_cmp_gt_f32_e32 vcc, v40, v70
	s_nop 1
	v_cndmask_b32_e32 v70, v70, v40, vcc
	v_cndmask_b32_e64 v53, v53, 4, vcc
	v_cmp_gt_f32_e32 vcc, v41, v70
	s_nop 1
	v_cndmask_b32_e32 v70, v70, v41, vcc
	v_cndmask_b32_e64 v53, v53, 5, vcc
	s_waitcnt lgkmcnt(12)
	v_cmp_gt_f32_e32 vcc, v42, v70
	s_nop 1
	v_cndmask_b32_e32 v70, v70, v42, vcc
	v_cndmask_b32_e64 v53, v53, 6, vcc
	v_cmp_gt_f32_e32 vcc, v43, v70
	s_nop 1
	v_cndmask_b32_e32 v70, v70, v43, vcc
	v_cndmask_b32_e64 v53, v53, 7, vcc
	s_waitcnt lgkmcnt(11)
	v_cmp_gt_f32_e32 vcc, v44, v70
	s_nop 1
	v_cndmask_b32_e32 v70, v70, v44, vcc
	v_cndmask_b32_e64 v53, v53, 8, vcc
	v_cmp_gt_f32_e32 vcc, v45, v70
	s_nop 1
	v_cndmask_b32_e32 v70, v70, v45, vcc
	v_cndmask_b32_e64 v53, v53, 9, vcc
	s_waitcnt lgkmcnt(10)
	v_cmp_gt_f32_e32 vcc, v46, v70
	s_nop 1
	v_cndmask_b32_e32 v70, v70, v46, vcc
	v_cndmask_b32_e64 v53, v53, 10, vcc
	v_cmp_gt_f32_e32 vcc, v47, v70
	s_nop 1
	v_cndmask_b32_e32 v70, v70, v47, vcc
	v_cndmask_b32_e64 v53, v53, 11, vcc
	s_waitcnt lgkmcnt(9)
	v_cmp_gt_f32_e32 vcc, v48, v70
	s_nop 1
	v_cndmask_b32_e32 v70, v70, v48, vcc
	v_cndmask_b32_e64 v53, v53, 12, vcc
	v_cmp_gt_f32_e32 vcc, v49, v70
	s_nop 1
	v_cndmask_b32_e32 v70, v70, v49, vcc
	v_cndmask_b32_e64 v53, v53, 13, vcc
	s_waitcnt lgkmcnt(8)
	v_cmp_gt_f32_e32 vcc, v50, v70
	s_nop 1
	v_cndmask_b32_e32 v70, v70, v50, vcc
	v_cndmask_b32_e64 v53, v53, 14, vcc
	v_cmp_gt_f32_e32 vcc, v51, v70
	s_nop 1
	v_cndmask_b32_e32 v70, v70, v51, vcc
	v_cndmask_b32_e64 v53, v53, 15, vcc
	s_waitcnt lgkmcnt(7)
	v_cmp_gt_f32_e32 vcc, v54, v70
	s_nop 1
	v_cndmask_b32_e32 v70, v70, v54, vcc
	v_cndmask_b32_e64 v53, v53, 16, vcc
	v_cmp_gt_f32_e32 vcc, v55, v70
	s_nop 1
	v_cndmask_b32_e32 v70, v70, v55, vcc
	v_cndmask_b32_e64 v53, v53, 17, vcc
	s_waitcnt lgkmcnt(6)
	v_cmp_gt_f32_e32 vcc, v56, v70
	s_nop 1
	v_cndmask_b32_e32 v70, v70, v56, vcc
	v_cndmask_b32_e64 v53, v53, 18, vcc
	v_cmp_gt_f32_e32 vcc, v57, v70
	s_nop 1
	v_cndmask_b32_e32 v70, v70, v57, vcc
	v_cndmask_b32_e64 v53, v53, 19, vcc
	s_waitcnt lgkmcnt(5)
	v_cmp_gt_f32_e32 vcc, v58, v70
	s_nop 1
	v_cndmask_b32_e32 v70, v70, v58, vcc
	v_cndmask_b32_e64 v53, v53, 20, vcc
	v_cmp_gt_f32_e32 vcc, v59, v70
	s_nop 1
	v_cndmask_b32_e32 v70, v70, v59, vcc
	v_cndmask_b32_e64 v53, v53, 21, vcc
	s_waitcnt lgkmcnt(4)
	v_cmp_gt_f32_e32 vcc, v60, v70
	s_nop 1
	v_cndmask_b32_e32 v70, v70, v60, vcc
	v_cndmask_b32_e64 v53, v53, 22, vcc
	v_cmp_gt_f32_e32 vcc, v61, v70
	s_nop 1
	v_cndmask_b32_e32 v70, v70, v61, vcc
	v_cndmask_b32_e64 v53, v53, 23, vcc
	s_waitcnt lgkmcnt(3)
	v_cmp_gt_f32_e32 vcc, v62, v70
	s_nop 1
	v_cndmask_b32_e32 v70, v70, v62, vcc
	v_cndmask_b32_e64 v53, v53, 24, vcc
	v_cmp_gt_f32_e32 vcc, v63, v70
	s_nop 1
	v_cndmask_b32_e32 v70, v70, v63, vcc
	v_cndmask_b32_e64 v53, v53, 25, vcc
	s_waitcnt lgkmcnt(2)
	v_cmp_gt_f32_e32 vcc, v64, v70
	s_nop 1
	v_cndmask_b32_e32 v70, v70, v64, vcc
	v_cndmask_b32_e64 v53, v53, 26, vcc
	v_cmp_gt_f32_e32 vcc, v65, v70
	s_nop 1
	v_cndmask_b32_e32 v70, v70, v65, vcc
	v_cndmask_b32_e64 v53, v53, 27, vcc
	s_waitcnt lgkmcnt(1)
	v_cmp_gt_f32_e32 vcc, v66, v70
	s_nop 1
	v_cndmask_b32_e32 v70, v70, v66, vcc
	v_cndmask_b32_e64 v53, v53, 28, vcc
	v_cmp_gt_f32_e32 vcc, v67, v70
	s_nop 1
	v_cndmask_b32_e32 v70, v70, v67, vcc
	v_cndmask_b32_e64 v53, v53, 29, vcc
	s_waitcnt lgkmcnt(0)
	v_cmp_gt_f32_e32 vcc, v68, v70
	s_nop 1
	v_cndmask_b32_e32 v70, v70, v68, vcc
	v_cndmask_b32_e64 v53, v53, 30, vcc
	v_cmp_ngt_f32_e32 vcc, v69, v70
	s_nop 1
	v_cndmask_b32_e32 v53, 31, v53, vcc
	v_lshlrev_b32_e64 v70, v53, 1
	v_cmp_lt_i32_e32 vcc, -1, v53
	s_nop 1
	v_cndmask_b32_e32 v70, 0, v70, vcc
	v_cmp_ne_u32_e32 vcc, 0, v53
	s_nop 1
	v_cndmask_b32_e32 v36, v215, v36, vcc
	v_cmp_ne_u32_e32 vcc, 1, v53
	s_nop 1
	v_cndmask_b32_e32 v37, v215, v37, vcc
	v_cmp_ne_u32_e32 vcc, 2, v53
	s_nop 1
	v_cndmask_b32_e32 v38, v215, v38, vcc
	v_cmp_ne_u32_e32 vcc, 3, v53
	s_nop 1
	v_cndmask_b32_e32 v39, v215, v39, vcc
	v_cmp_ne_u32_e32 vcc, 4, v53
	s_nop 1
	v_cndmask_b32_e32 v40, v215, v40, vcc
	v_cmp_ne_u32_e32 vcc, 5, v53
	s_nop 1
	v_cndmask_b32_e32 v41, v215, v41, vcc
	v_cmp_ne_u32_e32 vcc, 6, v53
	s_nop 1
	v_cndmask_b32_e32 v42, v215, v42, vcc
	v_cmp_ne_u32_e32 vcc, 7, v53
	s_nop 1
	v_cndmask_b32_e32 v43, v215, v43, vcc
	v_cmp_ne_u32_e32 vcc, 8, v53
	s_nop 1
	v_cndmask_b32_e32 v44, v215, v44, vcc
	v_cmp_ne_u32_e32 vcc, 9, v53
	s_nop 1
	v_cndmask_b32_e32 v45, v215, v45, vcc
	v_cmp_ne_u32_e32 vcc, 10, v53
	s_nop 1
	v_cndmask_b32_e32 v46, v215, v46, vcc
	v_cmp_ne_u32_e32 vcc, 11, v53
	s_nop 1
	v_cndmask_b32_e32 v47, v215, v47, vcc
	v_cmp_ne_u32_e32 vcc, 12, v53
	s_nop 1
	v_cndmask_b32_e32 v48, v215, v48, vcc
	v_cmp_ne_u32_e32 vcc, 13, v53
	s_nop 1
	v_cndmask_b32_e32 v49, v215, v49, vcc
	v_cmp_ne_u32_e32 vcc, 14, v53
	s_nop 1
	v_cndmask_b32_e32 v50, v215, v50, vcc
	v_cmp_ne_u32_e32 vcc, 15, v53
	s_nop 1
	v_cndmask_b32_e32 v51, v215, v51, vcc
	v_cmp_ne_u32_e32 vcc, 16, v53
	s_nop 1
	v_cndmask_b32_e32 v54, v215, v54, vcc
	v_cmp_ne_u32_e32 vcc, 17, v53
	s_nop 1
	v_cndmask_b32_e32 v55, v215, v55, vcc
	v_cmp_ne_u32_e32 vcc, 18, v53
	s_nop 1
	v_cndmask_b32_e32 v56, v215, v56, vcc
	v_cmp_ne_u32_e32 vcc, 19, v53
	s_nop 1
	v_cndmask_b32_e32 v57, v215, v57, vcc
	v_cmp_ne_u32_e32 vcc, 20, v53
	s_nop 1
	v_cndmask_b32_e32 v58, v215, v58, vcc
	v_cmp_ne_u32_e32 vcc, 21, v53
	s_nop 1
	v_cndmask_b32_e32 v59, v215, v59, vcc
	v_cmp_ne_u32_e32 vcc, 22, v53
	s_nop 1
	v_cndmask_b32_e32 v60, v215, v60, vcc
	v_cmp_ne_u32_e32 vcc, 23, v53
	s_nop 1
	v_cndmask_b32_e32 v61, v215, v61, vcc
	v_cmp_ne_u32_e32 vcc, 24, v53
	s_nop 1
	v_cndmask_b32_e32 v62, v215, v62, vcc
	v_cmp_ne_u32_e32 vcc, 25, v53
	s_nop 1
	v_cndmask_b32_e32 v63, v215, v63, vcc
	v_cmp_ne_u32_e32 vcc, 26, v53
	s_nop 1
	v_cndmask_b32_e32 v64, v215, v64, vcc
	v_cmp_ne_u32_e32 vcc, 27, v53
	s_nop 1
	v_cndmask_b32_e32 v65, v215, v65, vcc
	v_cmp_ne_u32_e32 vcc, 28, v53
	s_nop 1
	v_cndmask_b32_e32 v66, v215, v66, vcc
	v_cmp_ne_u32_e32 vcc, 29, v53
	s_nop 1
	v_cndmask_b32_e32 v67, v215, v67, vcc
	v_cmp_ne_u32_e32 vcc, 30, v53
	s_nop 1
	v_cndmask_b32_e32 v68, v215, v68, vcc
	v_cmp_ne_u32_e32 vcc, 31, v53
	s_nop 1
	v_cndmask_b32_e32 v53, v215, v69, vcc
	v_cmp_nlg_f32_e32 vcc, s73, v36
	v_lshl_or_b32 v69, 1, s47, v70
	s_nop 0
	v_cndmask_b32_e32 v71, v36, v215, vcc
	v_cndmask_b32_e64 v70, 0, -1, vcc
	v_cmp_gt_f32_e32 vcc, v37, v71
	s_nop 1
	v_cndmask_b32_e32 v71, v71, v37, vcc
	v_cndmask_b32_e64 v70, v70, 1, vcc
	v_cmp_gt_f32_e32 vcc, v38, v71
	s_nop 1
	v_cndmask_b32_e32 v71, v71, v38, vcc
	v_cndmask_b32_e64 v70, v70, 2, vcc
	v_cmp_gt_f32_e32 vcc, v39, v71
	s_nop 1
	v_cndmask_b32_e32 v71, v71, v39, vcc
	v_cndmask_b32_e64 v70, v70, 3, vcc
	v_cmp_gt_f32_e32 vcc, v40, v71
	s_nop 1
	v_cndmask_b32_e32 v71, v71, v40, vcc
	v_cndmask_b32_e64 v70, v70, 4, vcc
	v_cmp_gt_f32_e32 vcc, v41, v71
	s_nop 1
	v_cndmask_b32_e32 v71, v71, v41, vcc
	v_cndmask_b32_e64 v70, v70, 5, vcc
	v_cmp_gt_f32_e32 vcc, v42, v71
	s_nop 1
	v_cndmask_b32_e32 v71, v71, v42, vcc
	v_cndmask_b32_e64 v70, v70, 6, vcc
	v_cmp_gt_f32_e32 vcc, v43, v71
	s_nop 1
	v_cndmask_b32_e32 v71, v71, v43, vcc
	v_cndmask_b32_e64 v70, v70, 7, vcc
	v_cmp_gt_f32_e32 vcc, v44, v71
	s_nop 1
	v_cndmask_b32_e32 v71, v71, v44, vcc
	v_cndmask_b32_e64 v70, v70, 8, vcc
	v_cmp_gt_f32_e32 vcc, v45, v71
	s_nop 1
	v_cndmask_b32_e32 v71, v71, v45, vcc
	v_cndmask_b32_e64 v70, v70, 9, vcc
	v_cmp_gt_f32_e32 vcc, v46, v71
	s_nop 1
	v_cndmask_b32_e32 v71, v71, v46, vcc
	v_cndmask_b32_e64 v70, v70, 10, vcc
	v_cmp_gt_f32_e32 vcc, v47, v71
	s_nop 1
	v_cndmask_b32_e32 v71, v71, v47, vcc
	v_cndmask_b32_e64 v70, v70, 11, vcc
	v_cmp_gt_f32_e32 vcc, v48, v71
	s_nop 1
	v_cndmask_b32_e32 v71, v71, v48, vcc
	v_cndmask_b32_e64 v70, v70, 12, vcc
	v_cmp_gt_f32_e32 vcc, v49, v71
	s_nop 1
	v_cndmask_b32_e32 v71, v71, v49, vcc
	v_cndmask_b32_e64 v70, v70, 13, vcc
	v_cmp_gt_f32_e32 vcc, v50, v71
	s_nop 1
	v_cndmask_b32_e32 v71, v71, v50, vcc
	v_cndmask_b32_e64 v70, v70, 14, vcc
	v_cmp_gt_f32_e32 vcc, v51, v71
	s_nop 1
	v_cndmask_b32_e32 v71, v71, v51, vcc
	v_cndmask_b32_e64 v70, v70, 15, vcc
	v_cmp_gt_f32_e32 vcc, v54, v71
	s_nop 1
	v_cndmask_b32_e32 v71, v71, v54, vcc
	v_cndmask_b32_e64 v70, v70, 16, vcc
	v_cmp_gt_f32_e32 vcc, v55, v71
	s_nop 1
	v_cndmask_b32_e32 v71, v71, v55, vcc
	v_cndmask_b32_e64 v70, v70, 17, vcc
	v_cmp_gt_f32_e32 vcc, v56, v71
	s_nop 1
	v_cndmask_b32_e32 v71, v71, v56, vcc
	v_cndmask_b32_e64 v70, v70, 18, vcc
	v_cmp_gt_f32_e32 vcc, v57, v71
	s_nop 1
	v_cndmask_b32_e32 v71, v71, v57, vcc
	v_cndmask_b32_e64 v70, v70, 19, vcc
	v_cmp_gt_f32_e32 vcc, v58, v71
	s_nop 1
	v_cndmask_b32_e32 v71, v71, v58, vcc
	v_cndmask_b32_e64 v70, v70, 20, vcc
	v_cmp_gt_f32_e32 vcc, v59, v71
	s_nop 1
	v_cndmask_b32_e32 v71, v71, v59, vcc
	v_cndmask_b32_e64 v70, v70, 21, vcc
	v_cmp_gt_f32_e32 vcc, v60, v71
	s_nop 1
	v_cndmask_b32_e32 v71, v71, v60, vcc
	v_cndmask_b32_e64 v70, v70, 22, vcc
	v_cmp_gt_f32_e32 vcc, v61, v71
	s_nop 1
	v_cndmask_b32_e32 v71, v71, v61, vcc
	v_cndmask_b32_e64 v70, v70, 23, vcc
	v_cmp_gt_f32_e32 vcc, v62, v71
	s_nop 1
	v_cndmask_b32_e32 v71, v71, v62, vcc
	v_cndmask_b32_e64 v70, v70, 24, vcc
	v_cmp_gt_f32_e32 vcc, v63, v71
	s_nop 1
	v_cndmask_b32_e32 v71, v71, v63, vcc
	v_cndmask_b32_e64 v70, v70, 25, vcc
	v_cmp_gt_f32_e32 vcc, v64, v71
	s_nop 1
	v_cndmask_b32_e32 v71, v71, v64, vcc
	v_cndmask_b32_e64 v70, v70, 26, vcc
	v_cmp_gt_f32_e32 vcc, v65, v71
	s_nop 1
	v_cndmask_b32_e32 v71, v71, v65, vcc
	v_cndmask_b32_e64 v70, v70, 27, vcc
	v_cmp_gt_f32_e32 vcc, v66, v71
	s_nop 1
	v_cndmask_b32_e32 v71, v71, v66, vcc
	v_cndmask_b32_e64 v70, v70, 28, vcc
	v_cmp_gt_f32_e32 vcc, v67, v71
	s_nop 1
	v_cndmask_b32_e32 v71, v71, v67, vcc
	v_cndmask_b32_e64 v70, v70, 29, vcc
	v_cmp_gt_f32_e32 vcc, v68, v71
	s_nop 1
	v_cndmask_b32_e32 v71, v71, v68, vcc
	v_cndmask_b32_e64 v70, v70, 30, vcc
	v_cmp_ngt_f32_e32 vcc, v53, v71
	s_nop 1
	v_cndmask_b32_e32 v70, 31, v70, vcc
	v_lshlrev_b32_e64 v71, v70, 1
	v_cmp_lt_i32_e32 vcc, -1, v70
	s_nop 1
	v_cndmask_b32_e32 v71, 0, v71, vcc
	v_cmp_ne_u32_e32 vcc, 0, v70
	s_nop 1
	v_cndmask_b32_e32 v36, v215, v36, vcc
	v_cmp_ne_u32_e32 vcc, 1, v70
	s_nop 1
	v_cndmask_b32_e32 v37, v215, v37, vcc
	v_cmp_ne_u32_e32 vcc, 2, v70
	s_nop 1
	v_cndmask_b32_e32 v38, v215, v38, vcc
	v_cmp_ne_u32_e32 vcc, 3, v70
	s_nop 1
	v_cndmask_b32_e32 v39, v215, v39, vcc
	v_cmp_ne_u32_e32 vcc, 4, v70
	s_nop 1
	v_cndmask_b32_e32 v40, v215, v40, vcc
	v_cmp_ne_u32_e32 vcc, 5, v70
	s_nop 1
	v_cndmask_b32_e32 v41, v215, v41, vcc
	v_cmp_ne_u32_e32 vcc, 6, v70
	s_nop 1
	v_cndmask_b32_e32 v42, v215, v42, vcc
	v_cmp_ne_u32_e32 vcc, 7, v70
	s_nop 1
	v_cndmask_b32_e32 v43, v215, v43, vcc
	v_cmp_ne_u32_e32 vcc, 8, v70
	s_nop 1
	v_cndmask_b32_e32 v44, v215, v44, vcc
	v_cmp_ne_u32_e32 vcc, 9, v70
	s_nop 1
	v_cndmask_b32_e32 v45, v215, v45, vcc
	v_cmp_ne_u32_e32 vcc, 10, v70
	s_nop 1
	v_cndmask_b32_e32 v46, v215, v46, vcc
	v_cmp_ne_u32_e32 vcc, 11, v70
	s_nop 1
	v_cndmask_b32_e32 v47, v215, v47, vcc
	v_cmp_ne_u32_e32 vcc, 12, v70
	s_nop 1
	v_cndmask_b32_e32 v48, v215, v48, vcc
	v_cmp_ne_u32_e32 vcc, 13, v70
	s_nop 1
	v_cndmask_b32_e32 v49, v215, v49, vcc
	v_cmp_ne_u32_e32 vcc, 14, v70
	s_nop 1
	v_cndmask_b32_e32 v50, v215, v50, vcc
	v_cmp_ne_u32_e32 vcc, 15, v70
	s_nop 1
	v_cndmask_b32_e32 v51, v215, v51, vcc
	v_cmp_ne_u32_e32 vcc, 16, v70
	s_nop 1
	v_cndmask_b32_e32 v54, v215, v54, vcc
	v_cmp_ne_u32_e32 vcc, 17, v70
	s_nop 1
	v_cndmask_b32_e32 v55, v215, v55, vcc
	v_cmp_ne_u32_e32 vcc, 18, v70
	s_nop 1
	v_cndmask_b32_e32 v56, v215, v56, vcc
	v_cmp_ne_u32_e32 vcc, 19, v70
	s_nop 1
	v_cndmask_b32_e32 v57, v215, v57, vcc
	v_cmp_ne_u32_e32 vcc, 20, v70
	s_nop 1
	v_cndmask_b32_e32 v58, v215, v58, vcc
	v_cmp_ne_u32_e32 vcc, 21, v70
	s_nop 1
	v_cndmask_b32_e32 v59, v215, v59, vcc
	v_cmp_ne_u32_e32 vcc, 22, v70
	s_nop 1
	v_cndmask_b32_e32 v60, v215, v60, vcc
	v_cmp_ne_u32_e32 vcc, 23, v70
	s_nop 1
	v_cndmask_b32_e32 v61, v215, v61, vcc
	v_cmp_ne_u32_e32 vcc, 24, v70
	s_nop 1
	v_cndmask_b32_e32 v62, v215, v62, vcc
	v_cmp_ne_u32_e32 vcc, 25, v70
	s_nop 1
	v_cndmask_b32_e32 v63, v215, v63, vcc
	v_cmp_ne_u32_e32 vcc, 26, v70
	s_nop 1
	v_cndmask_b32_e32 v64, v215, v64, vcc
	v_cmp_ne_u32_e32 vcc, 27, v70
	s_nop 1
	v_cndmask_b32_e32 v65, v215, v65, vcc
	v_cmp_ne_u32_e32 vcc, 28, v70
	s_nop 1
	v_cndmask_b32_e32 v66, v215, v66, vcc
	v_cmp_ne_u32_e32 vcc, 29, v70
	s_nop 1
	v_cndmask_b32_e32 v67, v215, v67, vcc
	v_cmp_ne_u32_e32 vcc, 30, v70
	s_nop 1
	v_cndmask_b32_e32 v68, v215, v68, vcc
	v_cmp_ne_u32_e32 vcc, 31, v70
	s_nop 1
	v_cndmask_b32_e32 v53, v215, v53, vcc
	v_cmp_nlg_f32_e32 vcc, s73, v36
	s_nop 1
	v_cndmask_b32_e32 v36, v36, v215, vcc
	v_cndmask_b32_e64 v70, 0, -1, vcc
	v_cmp_gt_f32_e32 vcc, v37, v36
	s_nop 1
	v_cndmask_b32_e32 v36, v36, v37, vcc
	v_cndmask_b32_e64 v70, v70, 1, vcc
	v_cmp_gt_f32_e32 vcc, v38, v36
	s_nop 1
	v_cndmask_b32_e32 v36, v36, v38, vcc
	v_cndmask_b32_e64 v37, v70, 2, vcc
	v_cmp_gt_f32_e32 vcc, v39, v36
	s_nop 1
	v_cndmask_b32_e32 v36, v36, v39, vcc
	v_cndmask_b32_e64 v37, v37, 3, vcc
	v_cmp_gt_f32_e32 vcc, v40, v36
	s_nop 1
	v_cndmask_b32_e32 v36, v36, v40, vcc
	v_cndmask_b32_e64 v37, v37, 4, vcc
	v_cmp_gt_f32_e32 vcc, v41, v36
	s_nop 1
	v_cndmask_b32_e32 v36, v36, v41, vcc
	v_cndmask_b32_e64 v37, v37, 5, vcc
	v_cmp_gt_f32_e32 vcc, v42, v36
	s_nop 1
	v_cndmask_b32_e32 v36, v36, v42, vcc
	v_cndmask_b32_e64 v37, v37, 6, vcc
	v_cmp_gt_f32_e32 vcc, v43, v36
	s_nop 1
	v_cndmask_b32_e32 v36, v36, v43, vcc
	v_cndmask_b32_e64 v37, v37, 7, vcc
	v_cmp_gt_f32_e32 vcc, v44, v36
	s_nop 1
	v_cndmask_b32_e32 v36, v36, v44, vcc
	v_cndmask_b32_e64 v37, v37, 8, vcc
	v_cmp_gt_f32_e32 vcc, v45, v36
	s_nop 1
	v_cndmask_b32_e32 v36, v36, v45, vcc
	v_cndmask_b32_e64 v37, v37, 9, vcc
	v_cmp_gt_f32_e32 vcc, v46, v36
	s_nop 1
	v_cndmask_b32_e32 v36, v36, v46, vcc
	v_cndmask_b32_e64 v37, v37, 10, vcc
	v_cmp_gt_f32_e32 vcc, v47, v36
	s_nop 1
	v_cndmask_b32_e32 v36, v36, v47, vcc
	v_cndmask_b32_e64 v37, v37, 11, vcc
	v_cmp_gt_f32_e32 vcc, v48, v36
	s_nop 1
	v_cndmask_b32_e32 v36, v36, v48, vcc
	v_cndmask_b32_e64 v37, v37, 12, vcc
	v_cmp_gt_f32_e32 vcc, v49, v36
	s_nop 1
	v_cndmask_b32_e32 v36, v36, v49, vcc
	v_cndmask_b32_e64 v37, v37, 13, vcc
	v_cmp_gt_f32_e32 vcc, v50, v36
	s_nop 1
	v_cndmask_b32_e32 v36, v36, v50, vcc
	v_cndmask_b32_e64 v37, v37, 14, vcc
	v_cmp_gt_f32_e32 vcc, v51, v36
	s_nop 1
	v_cndmask_b32_e32 v36, v36, v51, vcc
	v_cndmask_b32_e64 v37, v37, 15, vcc
	v_cmp_gt_f32_e32 vcc, v54, v36
	s_nop 1
	v_cndmask_b32_e32 v36, v36, v54, vcc
	v_cndmask_b32_e64 v37, v37, 16, vcc
	v_cmp_gt_f32_e32 vcc, v55, v36
	s_nop 1
	v_cndmask_b32_e32 v36, v36, v55, vcc
	v_cndmask_b32_e64 v37, v37, 17, vcc
	v_cmp_gt_f32_e32 vcc, v56, v36
	s_nop 1
	v_cndmask_b32_e32 v36, v36, v56, vcc
	v_cndmask_b32_e64 v37, v37, 18, vcc
	v_cmp_gt_f32_e32 vcc, v57, v36
	s_nop 1
	v_cndmask_b32_e32 v36, v36, v57, vcc
	v_cndmask_b32_e64 v37, v37, 19, vcc
	v_cmp_gt_f32_e32 vcc, v58, v36
	s_nop 1
	v_cndmask_b32_e32 v36, v36, v58, vcc
	v_cndmask_b32_e64 v37, v37, 20, vcc
	v_cmp_gt_f32_e32 vcc, v59, v36
	s_nop 1
	v_cndmask_b32_e32 v36, v36, v59, vcc
	v_cndmask_b32_e64 v37, v37, 21, vcc
	v_cmp_gt_f32_e32 vcc, v60, v36
	s_nop 1
	v_cndmask_b32_e32 v36, v36, v60, vcc
	v_cndmask_b32_e64 v37, v37, 22, vcc
	v_cmp_gt_f32_e32 vcc, v61, v36
	s_nop 1
	v_cndmask_b32_e32 v36, v36, v61, vcc
	v_cndmask_b32_e64 v37, v37, 23, vcc
	v_cmp_gt_f32_e32 vcc, v62, v36
	s_nop 1
	v_cndmask_b32_e32 v36, v36, v62, vcc
	v_cndmask_b32_e64 v37, v37, 24, vcc
	v_cmp_gt_f32_e32 vcc, v63, v36
	s_nop 1
	v_cndmask_b32_e32 v36, v36, v63, vcc
	v_cndmask_b32_e64 v37, v37, 25, vcc
	v_cmp_gt_f32_e32 vcc, v64, v36
	s_nop 1
	v_cndmask_b32_e32 v36, v36, v64, vcc
	v_cndmask_b32_e64 v37, v37, 26, vcc
	v_cmp_gt_f32_e32 vcc, v65, v36
	s_nop 1
	v_cndmask_b32_e32 v36, v36, v65, vcc
	v_cndmask_b32_e64 v37, v37, 27, vcc
	v_cmp_gt_f32_e32 vcc, v66, v36
	s_nop 1
	v_cndmask_b32_e32 v36, v36, v66, vcc
	v_cndmask_b32_e64 v37, v37, 28, vcc
	v_cmp_gt_f32_e32 vcc, v67, v36
	s_nop 1
	v_cndmask_b32_e32 v36, v36, v67, vcc
	v_cndmask_b32_e64 v37, v37, 29, vcc
	v_cmp_gt_f32_e32 vcc, v68, v36
	s_nop 1
	v_cndmask_b32_e32 v36, v36, v68, vcc
	v_cndmask_b32_e64 v37, v37, 30, vcc
	v_cmp_ngt_f32_e32 vcc, v53, v36
	s_nop 1
	v_cndmask_b32_e32 v36, 31, v37, vcc
	v_lshlrev_b32_e64 v37, v36, 1
	v_cmp_lt_i32_e32 vcc, -1, v36
	s_nop 1
	v_cndmask_b32_e32 v36, 0, v37, vcc
	v_or3_b32 v36, v69, v71, v36
	ds_write_b32 v166, v36

.LBB0_130:
	v_cndmask_b32_e64 v53, 0, 1, s[24:25]
	v_cmp_ne_u32_e64 s[0:1], 1, v53
	s_andn2_b64 vcc, exec, s[24:25]
	s_cbranch_vccnz .LBB0_132
	s_cmp_eq_u32 s51, 0
	s_cbranch_scc1 .LBB0_132
	s_lshr_b32 s8, s51, 1
	s_sub_i32 s8, s47, s8
	s_lshl_b32 s9, s51, 7
	s_lshl_b32 s8, s8, 8
	s_and_b32 s9, s9, 0x80
	s_or_b32 s8, s8, s9
	s_ashr_i32 s9, s8, 31
	v_lshl_add_u64 v[4:5], v[140:141], 0, s[8:9]
	v_mov_b64_e32 v[6:7], s[88:89]
	v_lshl_add_u64 v[28:29], s[8:9], 1, v[118:119]
	v_mad_u64_u32 v[6:7], s[8:9], v4, s72, v[6:7]
	v_mad_i32_i24 v7, v5, s72, v7
	v_lshl_add_u64 v[4:5], v[6:7], 0, s[20:21]
	v_lshl_add_u64 v[30:31], v[4:5], 0, v[2:3]
	v_add_co_u32_e32 v4, vcc, s3, v30
	s_mov_b32 s8, 0x3d000
	s_nop 0
	v_addc_co_u32_e32 v5, vcc, 0, v31, vcc
	v_add_co_u32_e32 v12, vcc, s8, v30
	v_lshl_add_u64 v[8:9], v[28:29], 0, v[146:147]
	s_nop 0
	v_addc_co_u32_e32 v13, vcc, 0, v31, vcc
	v_add_co_u32_e32 v20, vcc, 0x79000, v30
	v_lshl_add_u64 v[16:17], v[28:29], 0, v[148:149]
	s_nop 0
	v_addc_co_u32_e32 v21, vcc, 0, v31, vcc
	v_add_co_u32_e32 v30, vcc, 0xb5000, v30
	v_lshl_add_u64 v[24:25], v[28:29], 0, v[150:151]
	s_nop 0
	v_addc_co_u32_e32 v31, vcc, 0, v31, vcc
	v_lshl_add_u64 v[32:33], v[28:29], 0, v[152:153]
	global_load_dwordx4 v[4:7], v[4:5], off offset:1024
	s_nop 0
	global_load_dwordx4 v[8:11], v[8:9], off
	s_nop 0
	global_load_dwordx4 v[12:15], v[12:13], off offset:1024
	s_nop 0
	global_load_dwordx4 v[16:19], v[16:17], off
	s_nop 0
	global_load_dwordx4 v[20:23], v[20:21], off offset:1024
	s_nop 0
	global_load_dwordx4 v[24:27], v[24:25], off
	s_nop 0
	global_load_dwordx4 v[28:31], v[30:31], off offset:1024
	s_nop 0
	global_load_dwordx4 v[32:35], v[32:33], off
